# all three norm row loops: last four xor-butterfly steps (8,4,2,1) done with v_add_f32_dpp row_ror instead of ds_bpermute round trips (bitwise-same sums)
# baseline (speedup 1.0000x reference)
; DI unsigned pack2(float a, float b) { f2_t v = {a, b}; return __builtin_bit_cast(unsigned, __builtin_convertvector(v, bf2_t)); }
; DI int otid() { int t = threadIdx.x; asm volatile("" : "+v"(t)); return t; }
; DI float wave_sum(float v) {
; #pragma unroll
;   for (int o = 32; o >= 1; o >>= 1) v += __shfl_xor(v, o);
;   return v;
; }
; template <int MODE>
; DI void phase_norm(const float* xin, const float* g, const float* modl, int sh_off, int sc_off, u16* hout, float* fout) {
;   const int tid = otid(); const int lane = tid & 63, w = tid >> 6;
;   for (int row = blockIdx.x * NWAVE + w; row < NTOK; row += gridDim.x * NWAVE) {
;     const int b = row >> 14;
;     const float4* xr = (const float4*)(xin + (size_t)row * 1024);
;     float4 v[4];
; #pragma unroll
;     for (int i = 0; i < 4; ++i) v[i] = xr[lane + i * 64];
;     float ss = 0.f;
; #pragma unroll
;     for (int i = 0; i < 4; ++i) ss += v[i].x * v[i].x + v[i].y * v[i].y + v[i].z * v[i].z + v[i].w * v[i].w;
;     ss = wave_sum(ss);
;     const float inv = rsqrtf(ss * (1.f / 1024.f) + 1e-6f);
; #pragma unroll
;     for (int i = 0; i < 4; ++i) {
;       const int col = (lane + i * 64) * 4;
;       const float4 g4 = *(const float4*)(g + col);
;       if (MODE == 0) {
;         const float4 sc4 = *(const float4*)(modl + b * 6144 + sc_off + col);
;         const float4 sh4 = *(const float4*)(modl + b * 6144 + sh_off + col);
;         float y0 = v[i].x * inv * g4.x * (1.f + sc4.x) + sh4.x;
;         float y1 = v[i].y * inv * g4.y * (1.f + sc4.y) + sh4.y;
;         float y2 = v[i].z * inv * g4.z * (1.f + sc4.z) + sh4.z;
;         float y3 = v[i].w * inv * g4.w * (1.f + sc4.w) + sh4.w;
;         *(uint2*)(hout + (size_t)row * 1024 + col) = make_uint2(pack2(y0, y1), pack2(y2, y3));
.LBB0_55:
	v_ashrrev_i32_e32 v3, 31, v2
	v_lshlrev_b64 v[38:39], 12, v[2:3]
	v_lshl_add_u64 v[50:51], v[6:7], 0, v[38:39]
	global_load_dwordx4 v[38:41], v[50:51], off
	global_load_dwordx4 v[42:45], v[50:51], off offset:1024
	global_load_dwordx4 v[46:49], v[50:51], off offset:2048
	s_nop 0
	global_load_dwordx4 v[50:53], v[50:51], off offset:3072
	v_ashrrev_i32_e32 v54, 14, v2
	v_mul_i32_i24_e32 v54, 0x1800, v54
	v_ashrrev_i32_e32 v55, 31, v54
	v_lshl_add_u64 v[62:63], v[54:55], 2, s[26:27]
	s_mov_b64 s[6:7], 0x1000
	v_lshl_add_u64 v[66:67], v[62:63], 0, s[6:7]
	v_lshl_add_u64 v[54:55], v[66:67], 0, v[0:1]
	global_load_dwordx4 v[54:57], v[54:55], off
	s_nop 0
	global_load_dwordx4 v[58:61], v[4:5], off
	v_lshl_add_u64 v[68:69], v[62:63], 0, v[0:1]
	global_load_dwordx4 v[62:65], v[68:69], off
	v_lshl_add_u64 v[122:123], v[66:67], 0, v[10:11]
	v_lshl_add_u64 v[124:125], v[66:67], 0, v[12:13]
	v_lshl_add_u64 v[126:127], v[66:67], 0, v[14:15]
	global_load_dwordx4 v[86:89], v[4:5], off offset:1024
	global_load_dwordx4 v[90:93], v[122:123], off
	global_load_dwordx4 v[94:97], v[68:69], off offset:1024
	global_load_dwordx4 v[98:101], v[4:5], off offset:2048
	global_load_dwordx4 v[102:105], v[124:125], off
	global_load_dwordx4 v[106:109], v[68:69], off offset:2048
	global_load_dwordx4 v[110:113], v[4:5], off offset:3072
	global_load_dwordx4 v[114:117], v[126:127], off
	global_load_dwordx4 v[118:121], v[68:69], off offset:3072
	s_waitcnt vmcnt(15)
	v_mov_b32_e32 v76, v39
	s_waitcnt vmcnt(14)
	v_mov_b32_e32 v77, v43
	v_mov_b32_e32 v74, v38
	v_mov_b32_e32 v75, v42
	s_waitcnt vmcnt(13)
	v_mov_b32_e32 v84, v47
	s_waitcnt vmcnt(12)
	v_mov_b32_e32 v85, v51
	v_pk_mul_f32 v[76:77], v[76:77], v[76:77]
	v_mov_b32_e32 v70, v40
	v_mov_b32_e32 v71, v44
	v_mov_b32_e32 v82, v46
	v_mov_b32_e32 v83, v50
	v_pk_mul_f32 v[84:85], v[84:85], v[84:85]
	v_pk_fma_f32 v[74:75], v[74:75], v[74:75], v[76:77]
	v_mov_b32_e32 v72, v41
	v_mov_b32_e32 v73, v45
	v_mov_b32_e32 v78, v48
	v_mov_b32_e32 v79, v52
	v_pk_fma_f32 v[76:77], v[82:83], v[82:83], v[84:85]
	v_pk_fma_f32 v[70:71], v[70:71], v[70:71], v[74:75]
	v_mov_b32_e32 v80, v49
	v_mov_b32_e32 v81, v53
	v_pk_fma_f32 v[74:75], v[78:79], v[78:79], v[76:77]
	v_pk_fma_f32 v[70:71], v[72:73], v[72:73], v[70:71]
	v_pk_fma_f32 v[72:73], v[80:81], v[80:81], v[74:75]
	v_add_f32_e32 v70, v70, v71
	v_add_f32_e32 v70, v70, v72
	v_add_f32_e32 v70, v70, v73
	ds_bpermute_b32 v71, v32, v70
	s_waitcnt vmcnt(11)
	v_pk_add_f32 v[54:55], v[54:55], 1.0 op_sel_hi:[1,0]
	v_pk_add_f32 v[56:57], v[56:57], 1.0 op_sel_hi:[1,0]
	s_waitcnt lgkmcnt(0)
	v_add_f32_e32 v70, v70, v71
	ds_bpermute_b32 v71, v33, v70
	s_waitcnt lgkmcnt(0)
	v_add_f32_e32 v70, v70, v71
	s_nop 1
	v_add_f32_dpp v70, v70, v70 row_ror:8 row_mask:0xf bank_mask:0xf
	s_nop 1
	v_add_f32_dpp v70, v70, v70 row_ror:4 row_mask:0xf bank_mask:0xf
	s_nop 1
	v_add_f32_dpp v72, v70, v70 row_ror:2 row_mask:0xf bank_mask:0xf
	v_lshlrev_b64 v[70:71], 11, v[2:3]
	v_lshl_add_u64 v[70:71], v[8:9], 0, v[70:71]
	v_add_u32_e32 v2, s3, v2
	s_nop 1
	v_add_f32_dpp v3, v72, v72 row_ror:1 row_mask:0xf bank_mask:0xf
	v_fmamk_f32 v3, v3, 0x3a800000, v225
	v_mul_f32_e32 v72, 0x4b800000, v3
	v_cmp_gt_f32_e32 vcc, s33, v3
	s_nop 1
	v_cndmask_b32_e32 v3, v3, v72, vcc
	v_rsq_f32_e32 v3, v3
	v_lshl_add_u64 v[72:73], v[66:67], 0, v[10:11]
	v_mul_f32_e32 v74, 0x45800000, v3
	v_cndmask_b32_e32 v74, v3, v74, vcc
	v_pk_mul_f32 v[38:39], v[38:39], v[74:75] op_sel_hi:[1,0]
	v_pk_mul_f32 v[40:41], v[40:41], v[74:75] op_sel_hi:[1,0]
	s_waitcnt vmcnt(10)
	v_pk_mul_f32 v[38:39], v[58:59], v[38:39]
	v_pk_mul_f32 v[40:41], v[60:61], v[40:41]
	s_waitcnt vmcnt(0)
	v_pk_fma_f32 v[38:39], v[54:55], v[38:39], v[62:63]
	v_pk_fma_f32 v[40:41], v[56:57], v[40:41], v[64:65]
	v_cvt_pk_bf16_f32 v38, v38, v39
	v_cvt_pk_bf16_f32 v39, v40, v41
	global_store_dwordx2 v[70:71], v[38:39], off
	s_nop 0
	v_pk_mul_f32 v[42:43], v[42:43], v[74:75] op_sel_hi:[1,0]
	v_pk_mul_f32 v[44:45], v[44:45], v[74:75] op_sel_hi:[1,0]
	v_lshl_add_u64 v[62:63], v[66:67], 0, v[12:13]
	v_pk_mul_f32 v[46:47], v[46:47], v[74:75] op_sel_hi:[1,0]
	v_pk_mul_f32 v[48:49], v[48:49], v[74:75] op_sel_hi:[1,0]
	v_pk_mul_f32 v[50:51], v[50:51], v[74:75] op_sel_hi:[1,0]
	v_pk_mul_f32 v[52:53], v[52:53], v[74:75] op_sel_hi:[1,0]
	v_cmp_lt_i32_e32 vcc, s94, v2
	s_or_b64 s[28:29], vcc, s[28:29]
	v_pk_mul_f32 v[38:39], v[42:43], v[86:87]
	v_pk_add_f32 v[42:43], v[90:91], 1.0 op_sel_hi:[1,0]
	v_pk_mul_f32 v[40:41], v[44:45], v[88:89]
	v_pk_add_f32 v[44:45], v[92:93], 1.0 op_sel_hi:[1,0]
	v_pk_fma_f32 v[38:39], v[38:39], v[42:43], v[94:95]
	v_pk_fma_f32 v[40:41], v[40:41], v[44:45], v[96:97]
	v_cvt_pk_bf16_f32 v38, v38, v39
	v_cvt_pk_bf16_f32 v39, v40, v41
	global_store_dwordx2 v[70:71], v[38:39], off offset:512
	s_nop 0
	v_lshl_add_u64 v[58:59], v[66:67], 0, v[14:15]
	v_pk_mul_f32 v[38:39], v[46:47], v[98:99]
	v_pk_add_f32 v[42:43], v[102:103], 1.0 op_sel_hi:[1,0]
	v_pk_mul_f32 v[40:41], v[48:49], v[100:101]
	v_pk_add_f32 v[44:45], v[104:105], 1.0 op_sel_hi:[1,0]
	v_pk_fma_f32 v[38:39], v[38:39], v[42:43], v[106:107]
	v_pk_fma_f32 v[40:41], v[40:41], v[44:45], v[108:109]
	v_cvt_pk_bf16_f32 v38, v38, v39
	v_cvt_pk_bf16_f32 v39, v40, v41
	global_store_dwordx2 v[70:71], v[38:39], off offset:1024
	s_nop 0
	v_pk_mul_f32 v[38:39], v[50:51], v[110:111]
	v_pk_add_f32 v[42:43], v[114:115], 1.0 op_sel_hi:[1,0]
	v_pk_mul_f32 v[40:41], v[52:53], v[112:113]
	v_pk_add_f32 v[44:45], v[116:117], 1.0 op_sel_hi:[1,0]
	v_pk_fma_f32 v[38:39], v[38:39], v[42:43], v[118:119]
	v_pk_fma_f32 v[40:41], v[40:41], v[44:45], v[120:121]
	v_cvt_pk_bf16_f32 v38, v38, v39
	v_cvt_pk_bf16_f32 v39, v40, v41
	global_store_dwordx2 v[70:71], v[38:39], off offset:1536
	s_andn2_b64 exec, exec, s[28:29]
	s_cbranch_execnz .LBB0_55

; DI unsigned pack2(float a, float b) { f2_t v = {a, b}; return __builtin_bit_cast(unsigned, __builtin_convertvector(v, bf2_t)); }
; DI int otid() { int t = threadIdx.x; asm volatile("" : "+v"(t)); return t; }
; DI float wave_sum(float v) {
; #pragma unroll
;   for (int o = 32; o >= 1; o >>= 1) v += __shfl_xor(v, o);
;   return v;
; }
; template <int MODE>
; DI void phase_norm(const float* xin, const float* g, const float* modl, int sh_off, int sc_off, u16* hout, float* fout) {
;   const int tid = otid(); const int lane = tid & 63, w = tid >> 6;
;   for (int row = blockIdx.x * NWAVE + w; row < NTOK; row += gridDim.x * NWAVE) {
;     const int b = row >> 14;
;     const float4* xr = (const float4*)(xin + (size_t)row * 1024);
;     float4 v[4];
; #pragma unroll
;     for (int i = 0; i < 4; ++i) v[i] = xr[lane + i * 64];
;     float ss = 0.f;
; #pragma unroll
;     for (int i = 0; i < 4; ++i) ss += v[i].x * v[i].x + v[i].y * v[i].y + v[i].z * v[i].z + v[i].w * v[i].w;
;     ss = wave_sum(ss);
;     const float inv = rsqrtf(ss * (1.f / 1024.f) + 1e-6f);
; #pragma unroll
;     for (int i = 0; i < 4; ++i) {
;       const int col = (lane + i * 64) * 4;
;       const float4 g4 = *(const float4*)(g + col);
;       if (MODE == 0) {
;         const float4 sc4 = *(const float4*)(modl + b * 6144 + sc_off + col);
;         const float4 sh4 = *(const float4*)(modl + b * 6144 + sh_off + col);
;         float y0 = v[i].x * inv * g4.x * (1.f + sc4.x) + sh4.x;
;         float y1 = v[i].y * inv * g4.y * (1.f + sc4.y) + sh4.y;
;         float y2 = v[i].z * inv * g4.z * (1.f + sc4.z) + sh4.z;
;         float y3 = v[i].w * inv * g4.w * (1.f + sc4.w) + sh4.w;
;         *(uint2*)(hout + (size_t)row * 1024 + col) = make_uint2(pack2(y0, y1), pack2(y2, y3));
.LBB0_597:
	v_ashrrev_i32_e32 v3, 31, v2
	v_lshlrev_b64 v[32:33], 12, v[2:3]
	v_lshl_add_u64 v[44:45], v[6:7], 0, v[32:33]
	global_load_dwordx4 v[32:35], v[44:45], off
	global_load_dwordx4 v[36:39], v[44:45], off offset:1024
	global_load_dwordx4 v[40:43], v[44:45], off offset:2048
	s_nop 0
	global_load_dwordx4 v[44:47], v[44:45], off offset:3072
	v_ashrrev_i32_e32 v11, 14, v2
	v_mul_i32_i24_e32 v48, 0x1800, v11
	v_ashrrev_i32_e32 v49, 31, v48
	v_lshl_add_u64 v[56:57], v[48:49], 2, s[24:25]
	s_mov_b64 s[6:7], 0x4000
	v_lshl_add_u64 v[60:61], v[56:57], 0, s[6:7]
	s_mov_b64 s[6:7], 0x3000
	v_lshl_add_u64 v[48:49], v[60:61], 0, v[0:1]
	v_lshl_add_u64 v[62:63], v[56:57], 0, s[6:7]
	global_load_dwordx4 v[48:51], v[48:49], off
	s_nop 0
	global_load_dwordx4 v[52:55], v[4:5], off
	v_lshl_add_u64 v[56:57], v[62:63], 0, v[0:1]
	global_load_dwordx4 v[56:59], v[56:57], off
	v_mov_b32_e32 v128, v10
	v_mov_b32_e32 v129, v1
	v_mov_b32_e32 v130, v12
	v_mov_b32_e32 v131, v1
	v_mov_b32_e32 v132, v14
	v_mov_b32_e32 v133, v1
	v_lshl_add_u64 v[134:135], v[60:61], 0, v[128:129]
	v_lshl_add_u64 v[136:137], v[62:63], 0, v[128:129]
	v_lshl_add_u64 v[138:139], v[60:61], 0, v[130:131]
	v_lshl_add_u64 v[140:141], v[62:63], 0, v[130:131]
	v_lshl_add_u64 v[142:143], v[60:61], 0, v[132:133]
	v_lshl_add_u64 v[144:145], v[62:63], 0, v[132:133]
	global_load_dwordx4 v[86:89], v[4:5], off offset:1024
	global_load_dwordx4 v[90:93], v[134:135], off
	global_load_dwordx4 v[94:97], v[136:137], off
	global_load_dwordx4 v[98:101], v[4:5], off offset:2048
	global_load_dwordx4 v[102:105], v[138:139], off
	global_load_dwordx4 v[106:109], v[140:141], off
	global_load_dwordx4 v[110:113], v[4:5], off offset:3072
	global_load_dwordx4 v[114:117], v[142:143], off
	global_load_dwordx4 v[118:121], v[144:145], off
	s_waitcnt vmcnt(15)
	v_mov_b32_e32 v70, v33
	s_waitcnt vmcnt(14)
	v_mov_b32_e32 v71, v37
	v_mov_b32_e32 v68, v32
	v_mov_b32_e32 v69, v36
	s_waitcnt vmcnt(13)
	v_mov_b32_e32 v78, v41
	s_waitcnt vmcnt(12)
	v_mov_b32_e32 v79, v45
	v_pk_mul_f32 v[70:71], v[70:71], v[70:71]
	v_mov_b32_e32 v64, v34
	v_mov_b32_e32 v65, v38
	v_mov_b32_e32 v76, v40
	v_mov_b32_e32 v77, v44
	v_pk_mul_f32 v[78:79], v[78:79], v[78:79]
	v_pk_fma_f32 v[68:69], v[68:69], v[68:69], v[70:71]
	v_mov_b32_e32 v66, v35
	v_mov_b32_e32 v67, v39
	v_mov_b32_e32 v72, v42
	v_mov_b32_e32 v73, v46
	v_pk_fma_f32 v[70:71], v[76:77], v[76:77], v[78:79]
	v_pk_fma_f32 v[64:65], v[64:65], v[64:65], v[68:69]
	v_mov_b32_e32 v74, v43
	v_mov_b32_e32 v75, v47
	v_pk_fma_f32 v[68:69], v[72:73], v[72:73], v[70:71]
	v_pk_fma_f32 v[64:65], v[66:67], v[66:67], v[64:65]
	v_pk_fma_f32 v[66:67], v[74:75], v[74:75], v[68:69]
	v_add_f32_e32 v11, v64, v65
	v_add_f32_e32 v11, v11, v66
	v_add_f32_e32 v11, v11, v67
	ds_bpermute_b32 v13, v242, v11
	v_lshlrev_b64 v[64:65], 11, v[2:3]
	s_waitcnt vmcnt(11)
	v_pk_add_f32 v[48:49], v[48:49], 1.0 op_sel_hi:[1,0]
	v_pk_add_f32 v[50:51], v[50:51], 1.0 op_sel_hi:[1,0]
	v_lshl_add_u64 v[64:65], v[8:9], 0, v[64:65]
	s_waitcnt lgkmcnt(0)
	v_add_f32_e32 v11, v11, v13
	ds_bpermute_b32 v13, v243, v11
	v_add_u32_e32 v2, s3, v2
	s_waitcnt lgkmcnt(0)
	v_add_f32_e32 v11, v11, v13
	s_nop 1
	v_add_f32_dpp v11, v11, v11 row_ror:8 row_mask:0xf bank_mask:0xf
	s_nop 1
	v_add_f32_dpp v11, v11, v11 row_ror:4 row_mask:0xf bank_mask:0xf
	s_nop 1
	v_add_f32_dpp v13, v11, v11 row_ror:2 row_mask:0xf bank_mask:0xf
	v_mov_b32_e32 v11, v1
	v_lshl_add_u64 v[66:67], v[60:61], 0, v[10:11]
	s_nop 1
	v_add_f32_dpp v3, v13, v13 row_ror:1 row_mask:0xf bank_mask:0xf
	v_fmamk_f32 v3, v3, 0x3a800000, v225
	v_mul_f32_e32 v13, 0x4b800000, v3
	v_cmp_gt_f32_e32 vcc, s33, v3
	v_mov_b32_e32 v15, v1
	s_nop 0
	v_cndmask_b32_e32 v3, v3, v13, vcc
	v_rsq_f32_e32 v3, v3
	s_nop 0
	v_mul_f32_e32 v13, 0x45800000, v3
	v_cndmask_b32_e32 v68, v3, v13, vcc
	v_pk_mul_f32 v[32:33], v[32:33], v[68:69] op_sel_hi:[1,0]
	v_pk_mul_f32 v[34:35], v[34:35], v[68:69] op_sel_hi:[1,0]
	s_waitcnt vmcnt(10)
	v_pk_mul_f32 v[32:33], v[52:53], v[32:33]
	v_pk_mul_f32 v[34:35], v[54:55], v[34:35]
	s_waitcnt vmcnt(0)
	v_pk_fma_f32 v[32:33], v[48:49], v[32:33], v[56:57]
	v_pk_fma_f32 v[34:35], v[50:51], v[34:35], v[58:59]
	v_cvt_pk_bf16_f32 v32, v32, v33
	v_cvt_pk_bf16_f32 v33, v34, v35
	global_store_dwordx2 v[64:65], v[32:33], off
	s_nop 0
	v_lshl_add_u64 v[52:53], v[62:63], 0, v[10:11]
	v_pk_mul_f32 v[36:37], v[36:37], v[68:69] op_sel_hi:[1,0]
	v_pk_mul_f32 v[38:39], v[38:39], v[68:69] op_sel_hi:[1,0]
	v_mov_b32_e32 v13, v1
	v_lshl_add_u64 v[56:57], v[60:61], 0, v[12:13]
	v_pk_mul_f32 v[40:41], v[40:41], v[68:69] op_sel_hi:[1,0]
	v_pk_mul_f32 v[42:43], v[42:43], v[68:69] op_sel_hi:[1,0]
	v_pk_mul_f32 v[44:45], v[44:45], v[68:69] op_sel_hi:[1,0]
	v_pk_mul_f32 v[46:47], v[46:47], v[68:69] op_sel_hi:[1,0]
	v_cmp_lt_i32_e32 vcc, s94, v2
	s_or_b64 s[26:27], vcc, s[26:27]
	v_pk_mul_f32 v[32:33], v[36:37], v[86:87]
	v_pk_add_f32 v[36:37], v[90:91], 1.0 op_sel_hi:[1,0]
	v_pk_mul_f32 v[34:35], v[38:39], v[88:89]
	v_pk_add_f32 v[38:39], v[92:93], 1.0 op_sel_hi:[1,0]
	v_pk_fma_f32 v[32:33], v[32:33], v[36:37], v[94:95]
	v_pk_fma_f32 v[34:35], v[34:35], v[38:39], v[96:97]
	v_cvt_pk_bf16_f32 v32, v32, v33
	v_cvt_pk_bf16_f32 v33, v34, v35
	global_store_dwordx2 v[64:65], v[32:33], off offset:512
	s_nop 0
	v_lshl_add_u64 v[48:49], v[62:63], 0, v[12:13]
	v_lshl_add_u64 v[52:53], v[60:61], 0, v[14:15]
	v_pk_mul_f32 v[32:33], v[40:41], v[98:99]
	v_pk_add_f32 v[36:37], v[102:103], 1.0 op_sel_hi:[1,0]
	v_pk_mul_f32 v[34:35], v[42:43], v[100:101]
	v_pk_add_f32 v[38:39], v[104:105], 1.0 op_sel_hi:[1,0]
	v_pk_fma_f32 v[32:33], v[32:33], v[36:37], v[106:107]
	v_pk_fma_f32 v[34:35], v[34:35], v[38:39], v[108:109]
	v_cvt_pk_bf16_f32 v32, v32, v33
	v_cvt_pk_bf16_f32 v33, v34, v35
	global_store_dwordx2 v[64:65], v[32:33], off offset:1024
	s_nop 0
	v_lshl_add_u64 v[40:41], v[62:63], 0, v[14:15]
	v_pk_mul_f32 v[32:33], v[44:45], v[110:111]
	v_pk_add_f32 v[36:37], v[114:115], 1.0 op_sel_hi:[1,0]
	v_pk_mul_f32 v[34:35], v[46:47], v[112:113]
	v_pk_add_f32 v[38:39], v[116:117], 1.0 op_sel_hi:[1,0]
	v_pk_fma_f32 v[32:33], v[32:33], v[36:37], v[118:119]
	v_pk_fma_f32 v[34:35], v[34:35], v[38:39], v[120:121]
	v_cvt_pk_bf16_f32 v32, v32, v33
	v_cvt_pk_bf16_f32 v33, v34, v35
	global_store_dwordx2 v[64:65], v[32:33], off offset:1536
	s_andn2_b64 exec, exec, s[26:27]
	s_cbranch_execnz .LBB0_597

; DI unsigned pack2(float a, float b) { f2_t v = {a, b}; return __builtin_bit_cast(unsigned, __builtin_convertvector(v, bf2_t)); }
; DI int otid() { int t = threadIdx.x; asm volatile("" : "+v"(t)); return t; }
; DI float wave_sum(float v) {
; #pragma unroll
;   for (int o = 32; o >= 1; o >>= 1) v += __shfl_xor(v, o);
;   return v;
; }
; template <int MODE>
; DI void phase_norm(const float* xin, const float* g, const float* modl, int sh_off, int sc_off, u16* hout, float* fout) {
;   const int tid = otid(); const int lane = tid & 63, w = tid >> 6;
;   for (int row = blockIdx.x * NWAVE + w; row < NTOK; row += gridDim.x * NWAVE) {
;     const int b = row >> 14;
;     const float4* xr = (const float4*)(xin + (size_t)row * 1024);
;     float4 v[4];
; #pragma unroll
;     for (int i = 0; i < 4; ++i) v[i] = xr[lane + i * 64];
;     float ss = 0.f;
; #pragma unroll
;     for (int i = 0; i < 4; ++i) ss += v[i].x * v[i].x + v[i].y * v[i].y + v[i].z * v[i].z + v[i].w * v[i].w;
;     ss = wave_sum(ss);
;     const float inv = rsqrtf(ss * (1.f / 1024.f) + 1e-6f);
; #pragma unroll
;     for (int i = 0; i < 4; ++i) {
;       const int col = (lane + i * 64) * 4;
;       const float4 g4 = *(const float4*)(g + col);
;       if (MODE == 0) {
;         const float4 sc4 = *(const float4*)(modl + b * 6144 + sc_off + col);
;         const float4 sh4 = *(const float4*)(modl + b * 6144 + sh_off + col);
;         float y0 = v[i].x * inv * g4.x * (1.f + sc4.x) + sh4.x;
;         float y1 = v[i].y * inv * g4.y * (1.f + sc4.y) + sh4.y;
;         float y2 = v[i].z * inv * g4.z * (1.f + sc4.z) + sh4.z;
;         float y3 = v[i].w * inv * g4.w * (1.f + sc4.w) + sh4.w;
;         *(uint2*)(hout + (size_t)row * 1024 + col) = make_uint2(pack2(y0, y1), pack2(y2, y3));
;       } else {
;         float4 y; y.x = v[i].x * inv * g4.x; y.y = v[i].y * inv * g4.y; y.z = v[i].z * inv * g4.z; y.w = v[i].w * inv * g4.w;
;         *(float4*)(fout + (size_t)row * 1024 + col) = y;
;       }
.LBB0_843:
	v_ashrrev_i32_e32 v1, 31, v0
	v_lshlrev_b64 v[10:11], 12, v[0:1]
	v_lshl_add_u64 v[30:31], s[6:7], 0, v[10:11]
	v_lshl_add_u64 v[32:33], v[30:31], 0, v[2:3]
	global_load_dwordx4 v[10:13], v[32:33], off
	global_load_dwordx4 v[14:17], v[32:33], off offset:1024
	global_load_dwordx4 v[18:21], v[32:33], off offset:2048
	global_load_dwordx4 v[22:25], v[32:33], off offset:3072
	v_lshl_add_u64 v[30:31], v[30:31], 0, v[6:7]
	v_add_u32_e32 v0, s3, v0
	s_waitcnt vmcnt(3)
	v_mov_b32_e32 v34, v11
	s_waitcnt vmcnt(2)
	v_mov_b32_e32 v35, v15
	v_mov_b32_e32 v32, v10
	v_mov_b32_e32 v33, v14
	s_waitcnt vmcnt(1)
	v_mov_b32_e32 v42, v19
	s_waitcnt vmcnt(0)
	v_mov_b32_e32 v43, v23
	v_pk_mul_f32 v[34:35], v[34:35], v[34:35]
	v_mov_b32_e32 v36, v12
	v_mov_b32_e32 v37, v16
	v_mov_b32_e32 v40, v18
	v_mov_b32_e32 v41, v22
	v_pk_mul_f32 v[42:43], v[42:43], v[42:43]
	v_pk_fma_f32 v[32:33], v[32:33], v[32:33], v[34:35]
	v_mov_b32_e32 v38, v13
	v_mov_b32_e32 v39, v17
	v_mov_b32_e32 v44, v20
	v_mov_b32_e32 v45, v24
	v_pk_fma_f32 v[34:35], v[40:41], v[40:41], v[42:43]
	v_pk_fma_f32 v[32:33], v[36:37], v[36:37], v[32:33]
	v_mov_b32_e32 v46, v21
	v_mov_b32_e32 v47, v25
	v_pk_fma_f32 v[34:35], v[44:45], v[44:45], v[34:35]
	v_pk_fma_f32 v[32:33], v[38:39], v[38:39], v[32:33]
	v_pk_fma_f32 v[34:35], v[46:47], v[46:47], v[34:35]
	v_add_f32_e32 v1, v32, v33
	v_add_f32_e32 v1, v1, v34
	v_add_f32_e32 v1, v1, v35
	ds_bpermute_b32 v9, v242, v1
	s_waitcnt lgkmcnt(0)
	v_add_f32_e32 v1, v1, v9
	ds_bpermute_b32 v9, v243, v1
	s_waitcnt lgkmcnt(0)
	v_add_f32_e32 v1, v1, v9
	s_nop 1
	v_add_f32_dpp v1, v1, v1 row_ror:8 row_mask:0xf bank_mask:0xf
	s_nop 1
	v_add_f32_dpp v1, v1, v1 row_ror:4 row_mask:0xf bank_mask:0xf
	s_nop 1
	v_add_f32_dpp v1, v1, v1 row_ror:2 row_mask:0xf bank_mask:0xf
	s_nop 1
	v_add_f32_dpp v1, v1, v1 row_ror:1 row_mask:0xf bank_mask:0xf
	v_fmamk_f32 v1, v1, 0x3a800000, v8
	v_mul_f32_e32 v9, 0x4b800000, v1
	v_cmp_gt_f32_e32 vcc, s2, v1
	s_nop 1
	v_cndmask_b32_e32 v1, v1, v9, vcc
	v_rsq_f32_e32 v1, v1
	s_nop 0
	v_mul_f32_e32 v9, 0x45800000, v1
	v_cndmask_b32_e32 v32, v1, v9, vcc
	v_pk_mul_f32 v[10:11], v[10:11], v[32:33] op_sel_hi:[1,0]
	v_pk_mul_f32 v[12:13], v[12:13], v[32:33] op_sel_hi:[1,0]
	v_pk_mul_f32 v[10:11], v[48:49], v[10:11]
	v_pk_mul_f32 v[12:13], v[50:51], v[12:13]
	global_store_dwordx4 v[30:31], v[10:13], off
	s_nop 1
	v_pk_mul_f32 v[14:15], v[14:15], v[32:33] op_sel_hi:[1,0]
	v_pk_mul_f32 v[16:17], v[16:17], v[32:33] op_sel_hi:[1,0]
	v_cmp_lt_i32_e32 vcc, s4, v0
	s_or_b64 s[0:1], vcc, s[0:1]
	v_pk_mul_f32 v[10:11], v[52:53], v[14:15]
	v_pk_mul_f32 v[12:13], v[54:55], v[16:17]
	global_store_dwordx4 v[30:31], v[10:13], off offset:1024
	s_nop 1
	v_pk_mul_f32 v[14:15], v[18:19], v[32:33] op_sel_hi:[1,0]
	v_pk_mul_f32 v[16:17], v[20:21], v[32:33] op_sel_hi:[1,0]
	v_pk_mul_f32 v[10:11], v[14:15], v[56:57]
	v_pk_mul_f32 v[12:13], v[16:17], v[58:59]
	global_store_dwordx4 v[30:31], v[10:13], off offset:2048
	s_nop 1
	v_pk_mul_f32 v[14:15], v[22:23], v[32:33] op_sel_hi:[1,0]
	v_pk_mul_f32 v[16:17], v[24:25], v[32:33] op_sel_hi:[1,0]
	v_pk_mul_f32 v[10:11], v[14:15], v[60:61]
	v_pk_mul_f32 v[12:13], v[16:17], v[62:63]
	global_store_dwordx4 v[30:31], v[10:13], off offset:3072
	s_nop 1
	s_andn2_b64 exec, exec, s[0:1]
	s_cbranch_execnz .LBB0_843
